# XCD-local fast path for SEAM4/SEAM5 when placement census shows each bx&7 group on one XCC (fallback: original barrier); WAR counter guards P6 out stores
# speedup vs baseline: 1.0115x; 1.0031x over previous
; #define LAS __attribute__((address_space(3)))
; __device__ __forceinline__ unsigned xb_add(unsigned* p, unsigned v) { return __hip_atomic_fetch_add(p, v, __ATOMIC_RELAXED, __HIP_MEMORY_SCOPE_AGENT); }
; __device__ __forceinline__ unsigned xb_xcc_id() { return (unsigned)__builtin_amdgcn_s_getreg((3 << 11) | 20) & 0xFu; }
; __device__ __forceinline__ XcdBarrier xcd_barrier_post(unsigned* bar, volatile LAS unsigned* st) {
;     XcdBarrier b; b.bar = bar; b.x = xb_xcc_id(); b.st = st;
;     if (threadIdx.x == 0) (void)xb_add(&bar[XB_XCNT(b.x)], 1u);
;     return b;
; __global__ void __launch_bounds__(512, 2) fwd_megakernel(Args a) {
;     ...
;     if (tid < 4) ((LAS unsigned*)(lds + 163328))[tid] = 0u;
;     __syncthreads();
;     const XcdBarrier bar = xcd_barrier_post((unsigned*)(ws + WS_BAR), (volatile LAS unsigned*)(lds + 163328));
.LBB0_2:
	s_load_dwordx2 s[82:83], s[0:1], 0x60
	s_load_dwordx8 s[72:79], s[0:1], 0x40
	v_and_b32_e32 v188, 0x3ff, v0
	v_cmp_gt_u32_e32 vcc, 4, v188
	s_and_saveexec_b64 s[6:7], vcc
	v_lshl_add_u32 v1, v188, 2, 0
	v_add_u32_e32 v1, 0x27e00, v1
	v_mov_b32_e32 v2, 0
	ds_write_b32 v1, v2
	s_or_b64 exec, exec, s[6:7]
	s_load_dword s33, s[0:1], 0x70
	s_waitcnt lgkmcnt(0)
	s_add_u32 s6, s78, 0x1f00000
	s_barrier
	s_addc_u32 s7, s79, 0
	s_getreg_b32 s3, hwreg(HW_REG_XCC_ID, 0, 4)
	v_writelane_b32 v248, s6, 0
	s_and_b32 s3, s3, 15
	v_cmp_eq_u32_e64 s[8:9], 0, v188
	v_writelane_b32 v248, s7, 1
	s_mov_b64 s[6:7], exec
	v_writelane_b32 v248, s8, 2
	s_nop 1
	v_writelane_b32 v248, s9, 3
	s_and_b64 s[8:9], s[6:7], s[8:9]
	s_mov_b64 exec, s[8:9]
	s_cbranch_execz .LBB0_7
	s_mov_b64 s[8:9], exec
	v_mbcnt_lo_u32_b32 v1, s8, 0
	v_mbcnt_hi_u32_b32 v1, s9, v1
	v_cmp_eq_u32_e32 vcc, 0, v1
	s_and_b64 s[10:11], exec, vcc
	s_mov_b64 exec, s[10:11]
	s_cbranch_execz .LBB0_7
	s_bcnt1_i32_b64 s8, s[8:9]
	s_lshl_b32 s10, s3, 8
	v_mov_b32_e32 v2, s8
	v_readlane_b32 s8, v248, 0
	v_mov_b32_e32 v1, s10
	v_readlane_b32 s9, v248, 1
	s_nop 4
	global_atomic_add v1, v2, s[8:9] offset:1024
	s_lshl_b32 s10, s2, 2
	s_add_u32 s10, s10, 0x3a00
	s_add_u32 s11, s3, 1
	v_mov_b32_e32 v3, s10
	v_mov_b32_e32 v4, s11
	global_store_dword v3, v4, s[8:9] sc1

; __device__ __forceinline__ unsigned xb_ld(unsigned* p)              { return __hip_atomic_load(p, __ATOMIC_RELAXED, __HIP_MEMORY_SCOPE_AGENT); }
; #define XB_SPIN(cond, bar) do { unsigned _sp = 0; while (cond) { __builtin_amdgcn_s_sleep(1); \
;     if ((++_sp & 255u) == 0u) { if (xb_ld(&(bar)[XB_TMO])) break; if (_sp > XB_SPIN_CAP) { atomicAdd(&(bar)[XB_TMO], 1u); break; } } } } while (0)
; __device__ __forceinline__ void xcd_barrier(const XcdBarrier& b) {
;     ...
;             XB_SPIN(xb_ld(&bar[XB_XGEN(b.x)]) == gen, bar);
;             __builtin_amdgcn_fence(__ATOMIC_ACQUIRE, "agent");
;             asm volatile("s_waitcnt vmcnt(0)" ::: "memory");
;         }
;     }
;     __syncthreads();
.Ls3_released:
	s_waitcnt vmcnt(0)
	buffer_inv sc1
	s_waitcnt vmcnt(0)
	s_branch .Ls3_close
.Ls3_other:
	s_mov_b64 exec, s[4:5]
	v_readfirstlane_b32 s6, v188
	s_nop 3
	s_cmp_lg_u32 s6, 64
	s_cbranch_scc1 .Ls3_close
	v_and_b32_e32 v0, 63, v188
	v_lshlrev_b32_e32 v1, 2, v0
	v_add_u32_e32 v1, 0x3a00, v1
	v_readlane_b32 s10, v248, 0
	v_readlane_b32 s11, v248, 1
	v_and_b32_e32 v6, 7, v0
	v_lshlrev_b32_e32 v6, 2, v6
	s_nop 4
	global_load_dword v2, v1, s[10:11] sc1
	global_load_dword v3, v1, s[10:11] offset:256 sc1
	global_load_dword v4, v1, s[10:11] offset:512 sc1
	global_load_dword v5, v1, s[10:11] offset:768 sc1
	s_waitcnt vmcnt(0)
	ds_bpermute_b32 v7, v6, v2
	s_waitcnt lgkmcnt(0)
	v_xor_b32_e32 v2, v2, v7
	v_xor_b32_e32 v3, v3, v7
	v_xor_b32_e32 v4, v4, v7
	v_xor_b32_e32 v5, v5, v7
	v_or3_b32 v2, v2, v3, v4
	v_or_b32_e32 v2, v2, v5
	v_mov_b32_e32 v8, 1
	v_lshlrev_b32_e32 v8, v7, v8
	v_cmp_ne_u32_e32 vcc, 0, v2
	v_cmp_eq_u32_e64 s[6:7], 0, v7
	s_or_b64 s[6:7], vcc, s[6:7]
	v_readlane_b32 s8, v8, 0
	v_readlane_b32 s9, v8, 1
	s_nop 1
	s_or_b32 s8, s8, s9
	v_readlane_b32 s9, v8, 2
	s_nop 1
	s_or_b32 s8, s8, s9
	v_readlane_b32 s9, v8, 3
	s_nop 1
	s_or_b32 s8, s8, s9
	v_readlane_b32 s9, v8, 4
	s_nop 1
	s_or_b32 s8, s8, s9
	v_readlane_b32 s9, v8, 5
	s_nop 1
	s_or_b32 s8, s8, s9
	v_readlane_b32 s9, v8, 6
	s_nop 1
	s_or_b32 s8, s8, s9
	v_readlane_b32 s9, v8, 7
	s_nop 1
	s_or_b32 s8, s8, s9
	s_bcnt1_i32_b32 s8, s8
	s_cmp_eq_u64 s[6:7], 0
	s_cselect_b32 s9, 1, 0
	s_cmp_eq_u32 s8, 8
	s_cselect_b32 s9, s9, 0
	v_mov_b32_e32 v2, s9
	v_mov_b32_e32 v3, 0x27e08
	ds_write_b32 v3, v2

; __device__ __forceinline__ unsigned xb_ld(unsigned* p)              { return __hip_atomic_load(p, __ATOMIC_RELAXED, __HIP_MEMORY_SCOPE_AGENT); }
; __device__ __forceinline__ unsigned xb_add(unsigned* p, unsigned v) { return __hip_atomic_fetch_add(p, v, __ATOMIC_RELAXED, __HIP_MEMORY_SCOPE_AGENT); }
; #define XB_SPIN(cond, bar) do { unsigned _sp = 0; while (cond) { __builtin_amdgcn_s_sleep(1); \
;     if ((++_sp & 255u) == 0u) { if (xb_ld(&(bar)[XB_TMO])) break; if (_sp > XB_SPIN_CAP) { atomicAdd(&(bar)[XB_TMO], 1u); break; } } } } while (0)
; __device__ __forceinline__ void xcd_barrier(const XcdBarrier& b) {
;     asm volatile("s_waitcnt vmcnt(0)" ::: "memory");
;     __syncthreads();
;     if (threadIdx.x == 0) {
;         unsigned* bar = b.bar;
;         __builtin_amdgcn_s_waitcnt(0);
;         unsigned nloc = b.st[0], nx = b.st[1];
;         if (nloc == 0u) { xcd_barrier_complete(bar, b.x, nloc, nx); b.st[0] = nloc; b.st[1] = nx; }
;         const unsigned old = xb_add(&bar[XB_XSUB(b.x)], 1u);
;         const unsigned gen = old / nloc;
;         if (old + 1u == (gen + 1u) * nloc) {
;             __builtin_amdgcn_fence(__ATOMIC_RELEASE, "agent");
;             asm volatile("s_waitcnt vmcnt(0)" ::: "memory");
;             const unsigned og = xb_add(&bar[XB_TOP], 1u);
;             const unsigned tg = og / nx;
;             if (og + 1u == (tg + 1u) * nx) xb_add(&bar[XB_TOPGEN], 1u);
;             else XB_SPIN(xb_ld(&bar[XB_TOPGEN]) == tg, bar);
;             __builtin_amdgcn_fence(__ATOMIC_ACQUIRE, "agent");
;             xb_add(&bar[XB_XGEN(b.x)], 1u);
;             asm volatile("s_waitcnt vmcnt(0)" ::: "memory");
;         } else {
;             XB_SPIN(xb_ld(&bar[XB_XGEN(b.x)]) == gen, bar);
;             __builtin_amdgcn_fence(__ATOMIC_ACQUIRE, "agent");
;             asm volatile("s_waitcnt vmcnt(0)" ::: "memory");
.LBB0_532:
	s_cmp_gt_i32 s83, 5
	s_cselect_b64 s[0:1], -1, 0
	s_and_b64 s[4:5], s[84:85], s[0:1]
	s_andn2_b64 vcc, exec, s[4:5]
	s_cbranch_vccnz .LBB0_586
	s_waitcnt vmcnt(0)
	s_waitcnt vmcnt(0) lgkmcnt(0)
	s_barrier
	s_mov_b64 s[4:5], exec
	v_readlane_b32 s6, v248, 2
	v_readlane_b32 s7, v248, 3
	s_and_b64 s[6:7], s[4:5], s[6:7]
	s_mov_b64 exec, s[6:7]
	s_cbranch_execz .LBB0_585
	v_mov_b32_e32 v0, 0x27e08
	ds_read_b32 v2, v0
	v_readlane_b32 s10, v248, 0
	v_readlane_b32 s11, v248, 1
	s_lshl_b32 s6, s3, 8
	v_mov_b32_e32 v4, 1
	s_add_u32 s6, s10, s6
	s_addc_u32 s7, s11, 0
	s_waitcnt lgkmcnt(0)
	v_readfirstlane_b32 s8, v2
	s_nop 3
	s_cmp_eq_u32 s8, 0
	s_cbranch_scc1 .Ls4_slow
	v_mov_b32_e32 v5, 0x1000
	global_atomic_add v6, v5, v4, s[6:7] offset:1024 sc0
	v_mov_b32_e32 v5, 0x2000
	s_mov_b32 s99, 0
	s_waitcnt vmcnt(0)
	v_lshrrev_b32_e32 v7, 5, v6
	v_and_b32_e32 v8, 31, v6
	v_cmp_eq_u32_e32 vcc, 31, v8
	s_cbranch_vccz .Ls4_spin
	buffer_wbl2 sc1
	s_waitcnt vmcnt(0)
	global_atomic_add v5, v4, s[6:7] offset:1024
	s_branch .Ls4_rel
.Ls4_spin:
	global_load_dword v12, v5, s[6:7] offset:1024 sc1
	s_waitcnt vmcnt(0)
	v_cmp_ne_u32_e32 vcc, v12, v7
	s_cbranch_vccnz .Ls4_rel
	s_add_u32 s99, s99, 1
	s_cmp_gt_u32 s99, 0x40000
	s_cbranch_scc1 .Ls4_rel
	s_sleep 1
	s_branch .Ls4_spin

; __device__ __forceinline__ unsigned xb_ld(unsigned* p)              { return __hip_atomic_load(p, __ATOMIC_RELAXED, __HIP_MEMORY_SCOPE_AGENT); }
; __device__ __forceinline__ void xcd_barrier_complete(unsigned* bar, unsigned x, unsigned& nloc, unsigned& nx) {
;     const unsigned G = gridDim.x * gridDim.y * gridDim.z;
;     unsigned sum, cnt, mine, sp = 0u;
;     for (;;) {
;         sum = 0u; cnt = 0u; mine = 0u;
; #pragma unroll
;         for (unsigned j = 0; j < 16; ++j) { const unsigned c = xb_ld(&bar[XB_XCNT(j)]); sum += c; cnt += (c > 0u) ? 1u : 0u; mine = (j == x) ? c : mine; }
;         if (sum == G) break;
;         __builtin_amdgcn_s_sleep(1);
;         if ((++sp & 255u) == 0u) { if (xb_ld(&bar[XB_TMO])) break; if (sp > XB_SPIN_CAP) { atomicAdd(&bar[XB_TMO], 1u); break; } }
;     }
;     nloc = mine > 0u ? mine : 1u; nx = cnt > 0u ? cnt : 1u;
; }
; __device__ __forceinline__ void xcd_barrier(const XcdBarrier& b) {
;     asm volatile("s_waitcnt vmcnt(0)" ::: "memory");
;     __syncthreads();
;     if (threadIdx.x == 0) {
;         unsigned* bar = b.bar;
;         __builtin_amdgcn_s_waitcnt(0);
;         unsigned nloc = b.st[0], nx = b.st[1];
;         if (nloc == 0u) { xcd_barrier_complete(bar, b.x, nloc, nx); b.st[0] = nloc; b.st[1] = nx; }
.Ls4_slow:
	s_add_i32 s6, 0, 0x27e00
	v_mov_b32_e32 v0, s6
	s_waitcnt vmcnt(0) expcnt(0) lgkmcnt(0)
	ds_read_b32 v2, v0
	s_add_i32 s6, 0, 0x27e04
	v_mov_b32_e32 v0, s6
	ds_read_b32 v0, v0
	s_waitcnt lgkmcnt(1)
	v_cmp_ne_u32_e32 vcc, 0, v2
	s_cbranch_vccnz .LBB0_549
	s_add_u32 s6, s78, 0x1f00200
	s_addc_u32 s7, s79, 0
	s_add_u32 s8, s78, 0x1f00400
	s_addc_u32 s9, s79, 0
	s_add_u32 s10, s78, 0x1f00500
	s_addc_u32 s11, s79, 0
	s_add_u32 s12, s78, 0x1f00600
	s_addc_u32 s13, s79, 0
	s_add_u32 s14, s78, 0x1f00700
	s_addc_u32 s15, s79, 0
	s_add_u32 s16, s78, 0x1f00800
	s_addc_u32 s17, s79, 0
	s_add_u32 s18, s78, 0x1f00900
	s_addc_u32 s19, s79, 0
	s_add_u32 s20, s78, 0x1f00a00
	s_addc_u32 s21, s79, 0
	s_add_u32 s22, s78, 0x1f00b00
	s_addc_u32 s23, s79, 0
	s_add_u32 s24, s78, 0x1f00c00
	s_addc_u32 s25, s79, 0
	s_add_u32 s26, s78, 0x1f00d00
	s_addc_u32 s27, s79, 0
	s_add_u32 s28, s78, 0x1f00e00
	s_addc_u32 s29, s79, 0
	s_add_u32 s30, s78, 0x1f00f00
	s_addc_u32 s31, s79, 0
	s_add_u32 s34, s78, 0x1f01000
	s_addc_u32 s35, s79, 0
	s_add_u32 s36, s78, 0x1f01100
	s_addc_u32 s37, s79, 0
	s_add_u32 s38, s78, 0x1f01200
	s_addc_u32 s39, s79, 0
	s_mul_i32 s48, s81, s33
	s_add_u32 s40, s78, 0x1f01300
	s_mul_i32 s48, s48, s80
	s_addc_u32 s41, s79, 0
	s_mov_b32 s49, 1
	v_mov_b32_e32 v16, 0
	s_branch .LBB0_537

; __device__ __forceinline__ unsigned xb_ld(unsigned* p)              { return __hip_atomic_load(p, __ATOMIC_RELAXED, __HIP_MEMORY_SCOPE_AGENT); }
; __device__ __forceinline__ unsigned xb_add(unsigned* p, unsigned v) { return __hip_atomic_fetch_add(p, v, __ATOMIC_RELAXED, __HIP_MEMORY_SCOPE_AGENT); }
; #define XB_SPIN(cond, bar) do { unsigned _sp = 0; while (cond) { __builtin_amdgcn_s_sleep(1); \
;     if ((++_sp & 255u) == 0u) { if (xb_ld(&(bar)[XB_TMO])) break; if (_sp > XB_SPIN_CAP) { atomicAdd(&(bar)[XB_TMO], 1u); break; } } } } while (0)
; __device__ __forceinline__ void xcd_barrier(const XcdBarrier& b) {
;     asm volatile("s_waitcnt vmcnt(0)" ::: "memory");
;     __syncthreads();
;     if (threadIdx.x == 0) {
;         unsigned* bar = b.bar;
;         __builtin_amdgcn_s_waitcnt(0);
;         unsigned nloc = b.st[0], nx = b.st[1];
;         if (nloc == 0u) { xcd_barrier_complete(bar, b.x, nloc, nx); b.st[0] = nloc; b.st[1] = nx; }
;         const unsigned old = xb_add(&bar[XB_XSUB(b.x)], 1u);
;         const unsigned gen = old / nloc;
;         if (old + 1u == (gen + 1u) * nloc) {
;             __builtin_amdgcn_fence(__ATOMIC_RELEASE, "agent");
;             asm volatile("s_waitcnt vmcnt(0)" ::: "memory");
;             const unsigned og = xb_add(&bar[XB_TOP], 1u);
;             const unsigned tg = og / nx;
;             if (og + 1u == (tg + 1u) * nx) xb_add(&bar[XB_TOPGEN], 1u);
;             else XB_SPIN(xb_ld(&bar[XB_TOPGEN]) == tg, bar);
;             __builtin_amdgcn_fence(__ATOMIC_ACQUIRE, "agent");
;             xb_add(&bar[XB_XGEN(b.x)], 1u);
;             asm volatile("s_waitcnt vmcnt(0)" ::: "memory");
;         } else {
;             XB_SPIN(xb_ld(&bar[XB_XGEN(b.x)]) == gen, bar);
;             __builtin_amdgcn_fence(__ATOMIC_ACQUIRE, "agent");
;             asm volatile("s_waitcnt vmcnt(0)" ::: "memory");
.LBB0_611:
	s_cmp_gt_i32 s83, 6
	s_cselect_b64 s[0:1], -1, 0
	s_and_b64 s[4:5], s[4:5], s[0:1]
	s_andn2_b64 vcc, exec, s[4:5]
	s_cbranch_vccnz .LBB0_665
	s_waitcnt vmcnt(0)
	s_waitcnt vmcnt(0) lgkmcnt(0)
	s_barrier
	s_mov_b64 s[4:5], exec
	v_readlane_b32 s6, v248, 2
	v_readlane_b32 s7, v248, 3
	s_and_b64 s[6:7], s[4:5], s[6:7]
	s_mov_b64 exec, s[6:7]
	s_cbranch_execz .LBB0_664
	v_mov_b32_e32 v0, 0x27e08
	ds_read_b32 v2, v0
	v_readlane_b32 s10, v248, 0
	v_readlane_b32 s11, v248, 1
	s_lshl_b32 s6, s3, 8
	v_mov_b32_e32 v4, 1
	s_add_u32 s6, s10, s6
	s_addc_u32 s7, s11, 0
	v_mov_b32_e32 v5, 0x3900
	s_nop 1
	global_atomic_add v5, v4, s[10:11]
	s_waitcnt lgkmcnt(0)
	v_readfirstlane_b32 s8, v2
	s_nop 3
	s_cmp_eq_u32 s8, 0
	s_cbranch_scc1 .Ls5_slow
	v_mov_b32_e32 v5, 0x1000
	global_atomic_add v6, v5, v4, s[6:7] offset:1024 sc0
	v_mov_b32_e32 v5, 0x2000
	s_mov_b32 s99, 0
	s_waitcnt vmcnt(0)
	v_lshrrev_b32_e32 v7, 5, v6
	v_and_b32_e32 v8, 31, v6
	v_cmp_eq_u32_e32 vcc, 31, v8
	s_cbranch_vccz .Ls5_spin
	global_atomic_add v5, v4, s[6:7] offset:1024
	s_branch .Ls5_rel

; __device__ __forceinline__ unsigned xb_ld(unsigned* p)              { return __hip_atomic_load(p, __ATOMIC_RELAXED, __HIP_MEMORY_SCOPE_AGENT); }
; __device__ __forceinline__ void xcd_barrier_complete(unsigned* bar, unsigned x, unsigned& nloc, unsigned& nx) {
;     const unsigned G = gridDim.x * gridDim.y * gridDim.z;
;     unsigned sum, cnt, mine, sp = 0u;
;     for (;;) {
;         sum = 0u; cnt = 0u; mine = 0u;
; #pragma unroll
;         for (unsigned j = 0; j < 16; ++j) { const unsigned c = xb_ld(&bar[XB_XCNT(j)]); sum += c; cnt += (c > 0u) ? 1u : 0u; mine = (j == x) ? c : mine; }
;         if (sum == G) break;
;         __builtin_amdgcn_s_sleep(1);
;         if ((++sp & 255u) == 0u) { if (xb_ld(&bar[XB_TMO])) break; if (sp > XB_SPIN_CAP) { atomicAdd(&bar[XB_TMO], 1u); break; } }
;     }
;     nloc = mine > 0u ? mine : 1u; nx = cnt > 0u ? cnt : 1u;
; }
; __device__ __forceinline__ void xcd_barrier(const XcdBarrier& b) {
;     asm volatile("s_waitcnt vmcnt(0)" ::: "memory");
;     __syncthreads();
;     if (threadIdx.x == 0) {
;         unsigned* bar = b.bar;
;         __builtin_amdgcn_s_waitcnt(0);
;         unsigned nloc = b.st[0], nx = b.st[1];
;         if (nloc == 0u) { xcd_barrier_complete(bar, b.x, nloc, nx); b.st[0] = nloc; b.st[1] = nx; }
.Ls5_slow:
	s_add_i32 s6, 0, 0x27e00
	v_mov_b32_e32 v0, s6
	s_waitcnt vmcnt(0) expcnt(0) lgkmcnt(0)
	ds_read_b32 v2, v0
	s_add_i32 s6, 0, 0x27e04
	v_mov_b32_e32 v0, s6
	ds_read_b32 v0, v0
	s_waitcnt lgkmcnt(1)
	v_cmp_ne_u32_e32 vcc, 0, v2
	s_cbranch_vccnz .LBB0_628
	s_add_u32 s6, s78, 0x1f00200
	s_addc_u32 s7, s79, 0
	s_add_u32 s8, s78, 0x1f00400
	s_addc_u32 s9, s79, 0
	s_add_u32 s10, s78, 0x1f00500
	s_addc_u32 s11, s79, 0
	s_add_u32 s12, s78, 0x1f00600
	s_addc_u32 s13, s79, 0
	s_add_u32 s14, s78, 0x1f00700
	s_addc_u32 s15, s79, 0
	s_add_u32 s16, s78, 0x1f00800
	s_addc_u32 s17, s79, 0
	s_add_u32 s18, s78, 0x1f00900
	s_addc_u32 s19, s79, 0
	s_add_u32 s20, s78, 0x1f00a00
	s_addc_u32 s21, s79, 0
	s_add_u32 s22, s78, 0x1f00b00
	s_addc_u32 s23, s79, 0
	s_add_u32 s24, s78, 0x1f00c00
	s_addc_u32 s25, s79, 0
	s_add_u32 s26, s78, 0x1f00d00
	s_addc_u32 s27, s79, 0
	s_add_u32 s28, s78, 0x1f00e00
	s_addc_u32 s29, s79, 0
	s_add_u32 s30, s78, 0x1f00f00
	s_addc_u32 s31, s79, 0
	s_add_u32 s34, s78, 0x1f01000
	s_addc_u32 s35, s79, 0
	s_add_u32 s36, s78, 0x1f01100
	s_addc_u32 s37, s79, 0
	s_add_u32 s38, s78, 0x1f01200
	s_addc_u32 s39, s79, 0
	s_mul_i32 s33, s81, s33
	s_add_u32 s40, s78, 0x1f01300
	s_mul_i32 s33, s33, s80
	s_addc_u32 s41, s79, 0
	s_mov_b32 s48, 1
	v_mov_b32_e32 v16, 0
	s_branch .LBB0_616

;     __device__ __forceinline__ void fused(f32x4 (&acc)[2][2][4][2], const Unit& u, int wr, int wc, int fr, int fq, PG8_LAS unsigned char* lds, int wid, int lane) const {
;     ...
;         if (tid == 0) {
;             __hip_atomic_fetch_add(cnt + 64 * u.pm, 1u, __ATOMIC_RELAXED, __HIP_MEMORY_SCOPE_AGENT);
;             unsigned sp = 0u; while (__hip_atomic_load(cnt + 64 * u.pm, __ATOMIC_RELAXED, __HIP_MEMORY_SCOPE_AGENT) < 4u) { __builtin_amdgcn_s_sleep(2); if (++sp > (1u << 22)) break; }
;             __builtin_amdgcn_fence(__ATOMIC_ACQUIRE, "agent"); asm volatile("s_waitcnt vmcnt(0)" ::: "memory"); }
.LBB0_709:
	s_or_b64 exec, exec, s[10:11]
	v_readlane_b32 s100, v248, 0
	v_readlane_b32 s101, v248, 1
	v_mov_b32_e32 v12, 0x3900
	s_nop 3
	global_load_dword v13, v12, s[100:101] sc1
	s_mov_b32 s10, 0x400001
	v_mov_b32_e32 v3, 0
	s_branch .LBB0_711

;     __device__ __forceinline__ void fused(f32x4 (&acc)[2][2][4][2], const Unit& u, int wr, int wc, int fr, int fq, PG8_LAS unsigned char* lds, int wid, int lane) const {
;     ...
;             unsigned sp = 0u; while (__hip_atomic_load(cnt + 64 * u.pm, __ATOMIC_RELAXED, __HIP_MEMORY_SCOPE_AGENT) < 4u) { __builtin_amdgcn_s_sleep(2); if (++sp > (1u << 22)) break; }
;             __builtin_amdgcn_fence(__ATOMIC_ACQUIRE, "agent"); asm volatile("s_waitcnt vmcnt(0)" ::: "memory"); }
;         __builtin_amdgcn_s_barrier(); asm volatile("" ::: "memory");
.LBB0_717:
	s_mov_b32 s10, 0
.Lw5_chk:
	v_cmp_lt_u32_e32 vcc, 0xff, v13
	s_cbranch_vccnz .Lw5_ok
	s_add_u32 s10, s10, 1
	s_cmp_gt_u32 s10, 0x40000
	s_cbranch_scc1 .Lw5_ok
	s_sleep 1
	global_load_dword v13, v12, s[100:101] sc1
	s_waitcnt vmcnt(0)
	s_branch .Lw5_chk
